# accumulator zero-init before each GEMM unit packed: 127 v_mov_b32 -> 1 + 63 v_pk_mov_b32 (7 sites) on top of p7a
# baseline (speedup 1.0000x reference)
;     __device__ __forceinline__ bool next(int i, Unit& u) const { if ((long)i * G + c >= nwg) return false; u.pm = 0; u.pn = 0; return true; }
;     ...
;         const bool has_next = S.next(ui + 1, nxt);
;         const char* nA0 = has_next ? (const char*)g.A + (size_t)nxt.pm * tstep : cA; const char* nB0 = has_next ? (const char*)g.Bt + (size_t)nxt.pn * tstep : cB;
;         int nkb = 0; if constexpr (Sched::SK) { if (has_next) nkb = nxt.kb; }
;         const char* nA = nA0 + (size_t)nkb * kstep; const char* nB = nB0 + (size_t)nkb * kstep;
;         for (int t = kb; t < ke; t += 2) {
;             const bool last = (t == ke - 2);
;             const char* a1 = cA + (size_t)(t + 1) * kstep;
;             const char* a2 = last ? nA : cA + (size_t)(t + 2) * kstep; const char* b2 = last ? nB : cB + (size_t)(t + 2) * kstep;
;             const char* a3 = a2 + kstep; const char* b3 = b2 + kstep;
;     ...
; #pragma unroll
;         for (int a = 0; a < 2; ++a)
; #pragma unroll
;             for (int b = 0; b < 2; ++b)
; #pragma unroll
;                 for (int m = 0; m < 4; ++m)
; #pragma unroll
;                     for (int n = 0; n < 2; ++n) acc[a][b][m][n] = (f32x4){0.f, 0.f, 0.f, 0.f};
.LBB0_224:
	s_ashr_i32 s23, s22, 31
	s_lshl_b64 s[68:69], s[22:23], 20
	s_add_u32 s68, s51, s68
	s_addc_u32 s69, s35, s69
	s_and_b64 s[70:71], s[2:3], exec
	s_cselect_b32 s23, s69, s87
	s_cselect_b32 vcc_lo, s68, s86
	s_ashr_i32 s21, s20, 31
	s_lshl_b64 s[70:71], s[20:21], 20
	s_add_u32 s70, s10, s70
	s_addc_u32 s71, s11, s71
	s_and_b64 s[74:75], s[2:3], exec
	s_cselect_b32 s21, s71, s89
	s_cselect_b32 vcc_hi, s70, s88
	s_add_u32 s86, s86, 0x80080
	s_addc_u32 s87, s87, 0
	s_add_u32 s74, s88, 0x100
	v_mov_b32_e32 v34, 0
	s_addc_u32 s75, s89, 0
	s_mov_b32 s76, -2
	v_mov_b32_e32 v35, v34
	v_pk_mov_b32 v[36:37], v[34:35], v[34:35]
	v_pk_mov_b32 v[38:39], v[34:35], v[34:35]
	v_pk_mov_b32 v[40:41], v[34:35], v[34:35]
	v_pk_mov_b32 v[50:51], v[34:35], v[34:35]
	v_pk_mov_b32 v[52:53], v[34:35], v[34:35]
	v_pk_mov_b32 v[54:55], v[34:35], v[34:35]
	v_pk_mov_b32 v[56:57], v[34:35], v[34:35]
	v_pk_mov_b32 v[66:67], v[34:35], v[34:35]
	v_pk_mov_b32 v[68:69], v[34:35], v[34:35]
	v_pk_mov_b32 v[70:71], v[34:35], v[34:35]
	v_pk_mov_b32 v[72:73], v[34:35], v[34:35]
	v_pk_mov_b32 v[82:83], v[34:35], v[34:35]
	v_pk_mov_b32 v[84:85], v[34:35], v[34:35]
	v_pk_mov_b32 v[86:87], v[34:35], v[34:35]
	v_pk_mov_b32 v[88:89], v[34:35], v[34:35]
	v_pk_mov_b32 v[42:43], v[34:35], v[34:35]
	v_pk_mov_b32 v[44:45], v[34:35], v[34:35]
	v_pk_mov_b32 v[46:47], v[34:35], v[34:35]
	v_pk_mov_b32 v[48:49], v[34:35], v[34:35]
	v_pk_mov_b32 v[58:59], v[34:35], v[34:35]
	v_pk_mov_b32 v[60:61], v[34:35], v[34:35]
	v_pk_mov_b32 v[62:63], v[34:35], v[34:35]
	v_pk_mov_b32 v[64:65], v[34:35], v[34:35]
	v_pk_mov_b32 v[74:75], v[34:35], v[34:35]
	v_pk_mov_b32 v[76:77], v[34:35], v[34:35]
	v_pk_mov_b32 v[78:79], v[34:35], v[34:35]
	v_pk_mov_b32 v[80:81], v[34:35], v[34:35]
	v_pk_mov_b32 v[90:91], v[34:35], v[34:35]
	v_pk_mov_b32 v[92:93], v[34:35], v[34:35]
	v_pk_mov_b32 v[94:95], v[34:35], v[34:35]
	v_pk_mov_b32 v[96:97], v[34:35], v[34:35]
	v_pk_mov_b32 v[98:99], v[34:35], v[34:35]
	v_pk_mov_b32 v[100:101], v[34:35], v[34:35]
	v_pk_mov_b32 v[102:103], v[34:35], v[34:35]
	v_pk_mov_b32 v[104:105], v[34:35], v[34:35]
	v_pk_mov_b32 v[114:115], v[34:35], v[34:35]
	v_pk_mov_b32 v[116:117], v[34:35], v[34:35]
	v_pk_mov_b32 v[118:119], v[34:35], v[34:35]
	v_pk_mov_b32 v[120:121], v[34:35], v[34:35]
	v_pk_mov_b32 v[130:131], v[34:35], v[34:35]
	v_pk_mov_b32 v[132:133], v[34:35], v[34:35]
	v_pk_mov_b32 v[134:135], v[34:35], v[34:35]
	v_pk_mov_b32 v[136:137], v[34:35], v[34:35]
	v_pk_mov_b32 v[146:147], v[34:35], v[34:35]
	v_pk_mov_b32 v[148:149], v[34:35], v[34:35]
	v_pk_mov_b32 v[150:151], v[34:35], v[34:35]
	v_pk_mov_b32 v[152:153], v[34:35], v[34:35]
	v_pk_mov_b32 v[106:107], v[34:35], v[34:35]
	v_pk_mov_b32 v[108:109], v[34:35], v[34:35]
	v_pk_mov_b32 v[110:111], v[34:35], v[34:35]
	v_pk_mov_b32 v[112:113], v[34:35], v[34:35]
	v_pk_mov_b32 v[122:123], v[34:35], v[34:35]
	v_pk_mov_b32 v[124:125], v[34:35], v[34:35]
	v_pk_mov_b32 v[126:127], v[34:35], v[34:35]
	v_pk_mov_b32 v[128:129], v[34:35], v[34:35]
	v_pk_mov_b32 v[138:139], v[34:35], v[34:35]
	v_pk_mov_b32 v[140:141], v[34:35], v[34:35]
	v_pk_mov_b32 v[142:143], v[34:35], v[34:35]
	v_pk_mov_b32 v[144:145], v[34:35], v[34:35]
	v_pk_mov_b32 v[154:155], v[34:35], v[34:35]
	v_pk_mov_b32 v[156:157], v[34:35], v[34:35]
	v_pk_mov_b32 v[158:159], v[34:35], v[34:35]
	v_pk_mov_b32 v[160:161], v[34:35], v[34:35]
	s_nop 0
	s_nop 0
	s_nop 0
	s_nop 0
	s_nop 0
	s_nop 0
	s_nop 0
	s_nop 0
	s_nop 0
	s_nop 0
	s_nop 0
	s_nop 0
	s_nop 0
	s_nop 0
	s_nop 0

;     ...
;         const char* nA = nA0 + (size_t)nkb * kstep; const char* nB = nB0 + (size_t)nkb * kstep;
;         for (int t = kb; t < ke; t += 2) {
;             const bool last = (t == ke - 2);
;             const char* a1 = cA + (size_t)(t + 1) * kstep;
;             const char* a2 = last ? nA : cA + (size_t)(t + 2) * kstep; const char* b2 = last ? nB : cB + (size_t)(t + 2) * kstep;
;             const char* a3 = a2 + kstep; const char* b3 = b2 + kstep;
;     ...
; #pragma unroll
;         for (int a = 0; a < 2; ++a)
; #pragma unroll
;             for (int b = 0; b < 2; ++b)
; #pragma unroll
;                 for (int m = 0; m < 4; ++m)
; #pragma unroll
;                     for (int n = 0; n < 2; ++n) acc[a][b][m][n] = (f32x4){0.f, 0.f, 0.f, 0.f};
.LBB0_305:
	s_add_u32 s4, s86, 0x158080
	s_addc_u32 s5, s87, 0
	s_add_u32 s27, s74, 0x100
	v_mov_b32_e32 v34, 0
	s_addc_u32 s76, s75, 0
	s_mov_b32 s77, -2
	v_mov_b32_e32 v35, v34
	v_pk_mov_b32 v[36:37], v[34:35], v[34:35]
	v_pk_mov_b32 v[38:39], v[34:35], v[34:35]
	v_pk_mov_b32 v[40:41], v[34:35], v[34:35]
	v_pk_mov_b32 v[50:51], v[34:35], v[34:35]
	v_pk_mov_b32 v[52:53], v[34:35], v[34:35]
	v_pk_mov_b32 v[54:55], v[34:35], v[34:35]
	v_pk_mov_b32 v[56:57], v[34:35], v[34:35]
	v_pk_mov_b32 v[66:67], v[34:35], v[34:35]
	v_pk_mov_b32 v[68:69], v[34:35], v[34:35]
	v_pk_mov_b32 v[70:71], v[34:35], v[34:35]
	v_pk_mov_b32 v[72:73], v[34:35], v[34:35]
	v_pk_mov_b32 v[82:83], v[34:35], v[34:35]
	v_pk_mov_b32 v[84:85], v[34:35], v[34:35]
	v_pk_mov_b32 v[86:87], v[34:35], v[34:35]
	v_pk_mov_b32 v[88:89], v[34:35], v[34:35]
	v_pk_mov_b32 v[42:43], v[34:35], v[34:35]
	v_pk_mov_b32 v[44:45], v[34:35], v[34:35]
	v_pk_mov_b32 v[46:47], v[34:35], v[34:35]
	v_pk_mov_b32 v[48:49], v[34:35], v[34:35]
	v_pk_mov_b32 v[58:59], v[34:35], v[34:35]
	v_pk_mov_b32 v[60:61], v[34:35], v[34:35]
	v_pk_mov_b32 v[62:63], v[34:35], v[34:35]
	v_pk_mov_b32 v[64:65], v[34:35], v[34:35]
	v_pk_mov_b32 v[74:75], v[34:35], v[34:35]
	v_pk_mov_b32 v[76:77], v[34:35], v[34:35]
	v_pk_mov_b32 v[78:79], v[34:35], v[34:35]
	v_pk_mov_b32 v[80:81], v[34:35], v[34:35]
	v_pk_mov_b32 v[90:91], v[34:35], v[34:35]
	v_pk_mov_b32 v[92:93], v[34:35], v[34:35]
	v_pk_mov_b32 v[94:95], v[34:35], v[34:35]
	v_pk_mov_b32 v[96:97], v[34:35], v[34:35]
	v_pk_mov_b32 v[98:99], v[34:35], v[34:35]
	v_pk_mov_b32 v[100:101], v[34:35], v[34:35]
	v_pk_mov_b32 v[102:103], v[34:35], v[34:35]
	v_pk_mov_b32 v[104:105], v[34:35], v[34:35]
	v_pk_mov_b32 v[114:115], v[34:35], v[34:35]
	v_pk_mov_b32 v[116:117], v[34:35], v[34:35]
	v_pk_mov_b32 v[118:119], v[34:35], v[34:35]
	v_pk_mov_b32 v[120:121], v[34:35], v[34:35]
	v_pk_mov_b32 v[130:131], v[34:35], v[34:35]
	v_pk_mov_b32 v[132:133], v[34:35], v[34:35]
	v_pk_mov_b32 v[134:135], v[34:35], v[34:35]
	v_pk_mov_b32 v[136:137], v[34:35], v[34:35]
	v_pk_mov_b32 v[146:147], v[34:35], v[34:35]
	v_pk_mov_b32 v[148:149], v[34:35], v[34:35]
	v_pk_mov_b32 v[150:151], v[34:35], v[34:35]
	v_pk_mov_b32 v[152:153], v[34:35], v[34:35]
	v_pk_mov_b32 v[106:107], v[34:35], v[34:35]
	v_pk_mov_b32 v[108:109], v[34:35], v[34:35]
	v_pk_mov_b32 v[110:111], v[34:35], v[34:35]
	v_pk_mov_b32 v[112:113], v[34:35], v[34:35]
	v_pk_mov_b32 v[122:123], v[34:35], v[34:35]
	v_pk_mov_b32 v[124:125], v[34:35], v[34:35]
	v_pk_mov_b32 v[126:127], v[34:35], v[34:35]
	v_pk_mov_b32 v[128:129], v[34:35], v[34:35]
	v_pk_mov_b32 v[138:139], v[34:35], v[34:35]
	v_pk_mov_b32 v[140:141], v[34:35], v[34:35]
	v_pk_mov_b32 v[142:143], v[34:35], v[34:35]
	v_pk_mov_b32 v[144:145], v[34:35], v[34:35]
	v_pk_mov_b32 v[154:155], v[34:35], v[34:35]
	v_pk_mov_b32 v[156:157], v[34:35], v[34:35]
	v_pk_mov_b32 v[158:159], v[34:35], v[34:35]
	v_pk_mov_b32 v[160:161], v[34:35], v[34:35]

;     __device__ __forceinline__ bool next(int i, Unit& u) const { if ((long)i * G + c >= nwg) return false; u.pm = 0; u.pn = 0; return true; }
;     ...
;         const bool has_next = S.next(ui + 1, nxt);
;         const char* nA0 = has_next ? (const char*)g.A + (size_t)nxt.pm * tstep : cA; const char* nB0 = has_next ? (const char*)g.Bt + (size_t)nxt.pn * tstep : cB;
;         int nkb = 0; if constexpr (Sched::SK) { if (has_next) nkb = nxt.kb; }
;         const char* nA = nA0 + (size_t)nkb * kstep; const char* nB = nB0 + (size_t)nkb * kstep;
;         for (int t = kb; t < ke; t += 2) {
;             const bool last = (t == ke - 2);
;             const char* a1 = cA + (size_t)(t + 1) * kstep;
;             const char* a2 = last ? nA : cA + (size_t)(t + 2) * kstep; const char* b2 = last ? nB : cB + (size_t)(t + 2) * kstep;
;             const char* a3 = a2 + kstep; const char* b3 = b2 + kstep;
;     ...
; #pragma unroll
;         for (int a = 0; a < 2; ++a)
; #pragma unroll
;             for (int b = 0; b < 2; ++b)
; #pragma unroll
;                 for (int m = 0; m < 4; ++m)
; #pragma unroll
;                     for (int n = 0; n < 2; ++n) acc[a][b][m][n] = (f32x4){0.f, 0.f, 0.f, 0.f};
.LBB0_504:
	s_ashr_i32 s19, s18, 31
	s_lshl_b64 s[20:21], s[18:19], 20
	s_add_u32 s20, s27, s20
	s_addc_u32 s21, s34, s21
	s_and_b64 s[22:23], s[2:3], exec
	s_cselect_b32 s19, s21, s75
	s_cselect_b32 s95, s20, s74
	s_ashr_i32 s17, s16, 31
	s_lshl_b64 s[22:23], s[16:17], 20
	s_add_u32 s22, s84, s22
	s_addc_u32 s23, s85, s23
	s_and_b64 s[78:79], s[2:3], exec
	s_cselect_b32 s17, s23, s77
	s_cselect_b32 s96, s22, s76
	s_add_u32 s74, s74, 0x80080
	s_addc_u32 s75, s75, 0
	s_add_u32 s80, s76, 0x100
	v_mov_b32_e32 v34, 0
	s_addc_u32 s81, s77, 0
	s_mov_b32 s82, -2
	v_mov_b32_e32 v35, v34
	v_pk_mov_b32 v[36:37], v[34:35], v[34:35]
	v_pk_mov_b32 v[38:39], v[34:35], v[34:35]
	v_pk_mov_b32 v[40:41], v[34:35], v[34:35]
	v_pk_mov_b32 v[46:47], v[34:35], v[34:35]
	v_pk_mov_b32 v[48:49], v[34:35], v[34:35]
	v_pk_mov_b32 v[54:55], v[34:35], v[34:35]
	v_pk_mov_b32 v[56:57], v[34:35], v[34:35]
	v_pk_mov_b32 v[62:63], v[34:35], v[34:35]
	v_pk_mov_b32 v[64:65], v[34:35], v[34:35]
	v_pk_mov_b32 v[70:71], v[34:35], v[34:35]
	v_pk_mov_b32 v[72:73], v[34:35], v[34:35]
	v_pk_mov_b32 v[78:79], v[34:35], v[34:35]
	v_pk_mov_b32 v[80:81], v[34:35], v[34:35]
	v_pk_mov_b32 v[86:87], v[34:35], v[34:35]
	v_pk_mov_b32 v[88:89], v[34:35], v[34:35]
	v_pk_mov_b32 v[42:43], v[34:35], v[34:35]
	v_pk_mov_b32 v[44:45], v[34:35], v[34:35]
	v_pk_mov_b32 v[50:51], v[34:35], v[34:35]
	v_pk_mov_b32 v[52:53], v[34:35], v[34:35]
	v_pk_mov_b32 v[58:59], v[34:35], v[34:35]
	v_pk_mov_b32 v[60:61], v[34:35], v[34:35]
	v_pk_mov_b32 v[66:67], v[34:35], v[34:35]
	v_pk_mov_b32 v[68:69], v[34:35], v[34:35]
	v_pk_mov_b32 v[74:75], v[34:35], v[34:35]
	v_pk_mov_b32 v[76:77], v[34:35], v[34:35]
	v_pk_mov_b32 v[82:83], v[34:35], v[34:35]
	v_pk_mov_b32 v[84:85], v[34:35], v[34:35]
	v_pk_mov_b32 v[90:91], v[34:35], v[34:35]
	v_pk_mov_b32 v[92:93], v[34:35], v[34:35]
	v_pk_mov_b32 v[94:95], v[34:35], v[34:35]
	v_pk_mov_b32 v[96:97], v[34:35], v[34:35]
	v_pk_mov_b32 v[98:99], v[34:35], v[34:35]
	v_pk_mov_b32 v[100:101], v[34:35], v[34:35]
	v_pk_mov_b32 v[102:103], v[34:35], v[34:35]
	v_pk_mov_b32 v[104:105], v[34:35], v[34:35]
	v_pk_mov_b32 v[110:111], v[34:35], v[34:35]
	v_pk_mov_b32 v[112:113], v[34:35], v[34:35]
	v_pk_mov_b32 v[118:119], v[34:35], v[34:35]
	v_pk_mov_b32 v[120:121], v[34:35], v[34:35]
	v_pk_mov_b32 v[126:127], v[34:35], v[34:35]
	v_pk_mov_b32 v[128:129], v[34:35], v[34:35]
	v_pk_mov_b32 v[134:135], v[34:35], v[34:35]
	v_pk_mov_b32 v[136:137], v[34:35], v[34:35]
	v_pk_mov_b32 v[142:143], v[34:35], v[34:35]
	v_pk_mov_b32 v[144:145], v[34:35], v[34:35]
	v_pk_mov_b32 v[150:151], v[34:35], v[34:35]
	v_pk_mov_b32 v[152:153], v[34:35], v[34:35]
	v_pk_mov_b32 v[106:107], v[34:35], v[34:35]
	v_pk_mov_b32 v[108:109], v[34:35], v[34:35]
	v_pk_mov_b32 v[114:115], v[34:35], v[34:35]
	v_pk_mov_b32 v[116:117], v[34:35], v[34:35]
	v_pk_mov_b32 v[122:123], v[34:35], v[34:35]
	v_pk_mov_b32 v[124:125], v[34:35], v[34:35]
	v_pk_mov_b32 v[130:131], v[34:35], v[34:35]
	v_pk_mov_b32 v[132:133], v[34:35], v[34:35]
	v_pk_mov_b32 v[138:139], v[34:35], v[34:35]
	v_pk_mov_b32 v[140:141], v[34:35], v[34:35]
	v_pk_mov_b32 v[146:147], v[34:35], v[34:35]
	v_pk_mov_b32 v[148:149], v[34:35], v[34:35]
	v_pk_mov_b32 v[154:155], v[34:35], v[34:35]
	v_pk_mov_b32 v[156:157], v[34:35], v[34:35]
	v_pk_mov_b32 v[158:159], v[34:35], v[34:35]
	v_pk_mov_b32 v[160:161], v[34:35], v[34:35]
	s_nop 0
	s_nop 0
	s_nop 0

;     __device__ __forceinline__ bool next(int i, Unit& u) const { if ((long)i * G + c >= nwg) return false; u.pm = 0; u.pn = 0; return true; }
;     ...
;         const bool has_next = S.next(ui + 1, nxt);
;         const char* nA0 = has_next ? (const char*)g.A + (size_t)nxt.pm * tstep : cA; const char* nB0 = has_next ? (const char*)g.Bt + (size_t)nxt.pn * tstep : cB;
;         int nkb = 0; if constexpr (Sched::SK) { if (has_next) nkb = nxt.kb; }
;         const char* nA = nA0 + (size_t)nkb * kstep; const char* nB = nB0 + (size_t)nkb * kstep;
;         for (int t = kb; t < ke; t += 2) {
;             const bool last = (t == ke - 2);
;             const char* a1 = cA + (size_t)(t + 1) * kstep;
;             const char* a2 = last ? nA : cA + (size_t)(t + 2) * kstep; const char* b2 = last ? nB : cB + (size_t)(t + 2) * kstep;
;             const char* a3 = a2 + kstep; const char* b3 = b2 + kstep;
;     ...
; #pragma unroll
;         for (int a = 0; a < 2; ++a)
; #pragma unroll
;             for (int b = 0; b < 2; ++b)
; #pragma unroll
;                 for (int m = 0; m < 4; ++m)
; #pragma unroll
;                     for (int n = 0; n < 2; ++n) acc[a][b][m][n] = (f32x4){0.f, 0.f, 0.f, 0.f};
.LBB0_520:
	s_ashr_i32 s17, s16, 31
	s_lshl_b64 s[18:19], s[16:17], 21
	s_add_u32 s18, s51, s18
	s_addc_u32 s19, s35, s19
	s_and_b64 s[20:21], s[2:3], exec
	s_cselect_b32 s17, s19, s73
	s_cselect_b32 s80, s18, s72
	s_ashr_i32 s15, s14, 31
	s_lshl_b64 s[20:21], s[14:15], 21
	s_add_u32 s20, s34, s20
	s_addc_u32 s21, s78, s21
	s_and_b64 s[76:77], s[2:3], exec
	s_cselect_b32 s15, s21, s75
	s_cselect_b32 s81, s20, s74
	s_add_u32 s72, s72, 0x100080
	s_addc_u32 s73, s73, 0
	s_add_u32 s82, s74, 0x100
	v_mov_b32_e32 v2, 0
	s_addc_u32 s83, s75, 0
	s_mov_b32 s91, -2
	v_mov_b32_e32 v3, v2
	v_pk_mov_b32 v[4:5], v[2:3], v[2:3]
	v_pk_mov_b32 v[6:7], v[2:3], v[2:3]
	v_pk_mov_b32 v[8:9], v[2:3], v[2:3]
	v_pk_mov_b32 v[10:11], v[2:3], v[2:3]
	v_pk_mov_b32 v[12:13], v[2:3], v[2:3]
	v_pk_mov_b32 v[18:19], v[2:3], v[2:3]
	v_pk_mov_b32 v[20:21], v[2:3], v[2:3]
	v_pk_mov_b32 v[26:27], v[2:3], v[2:3]
	v_pk_mov_b32 v[28:29], v[2:3], v[2:3]
	v_pk_mov_b32 v[34:35], v[2:3], v[2:3]
	v_pk_mov_b32 v[36:37], v[2:3], v[2:3]
	v_pk_mov_b32 v[42:43], v[2:3], v[2:3]
	v_pk_mov_b32 v[44:45], v[2:3], v[2:3]
	v_pk_mov_b32 v[50:51], v[2:3], v[2:3]
	v_pk_mov_b32 v[52:53], v[2:3], v[2:3]
	v_pk_mov_b32 v[14:15], v[2:3], v[2:3]
	v_pk_mov_b32 v[16:17], v[2:3], v[2:3]
	v_pk_mov_b32 v[22:23], v[2:3], v[2:3]
	v_pk_mov_b32 v[24:25], v[2:3], v[2:3]
	v_pk_mov_b32 v[30:31], v[2:3], v[2:3]
	v_pk_mov_b32 v[32:33], v[2:3], v[2:3]
	v_pk_mov_b32 v[38:39], v[2:3], v[2:3]
	v_pk_mov_b32 v[40:41], v[2:3], v[2:3]
	v_pk_mov_b32 v[46:47], v[2:3], v[2:3]
	v_pk_mov_b32 v[48:49], v[2:3], v[2:3]
	v_pk_mov_b32 v[54:55], v[2:3], v[2:3]
	v_pk_mov_b32 v[56:57], v[2:3], v[2:3]
	v_pk_mov_b32 v[58:59], v[2:3], v[2:3]
	v_pk_mov_b32 v[60:61], v[2:3], v[2:3]
	v_pk_mov_b32 v[62:63], v[2:3], v[2:3]
	v_pk_mov_b32 v[64:65], v[2:3], v[2:3]
	v_pk_mov_b32 v[66:67], v[2:3], v[2:3]
	v_pk_mov_b32 v[68:69], v[2:3], v[2:3]
	v_pk_mov_b32 v[70:71], v[2:3], v[2:3]
	v_pk_mov_b32 v[72:73], v[2:3], v[2:3]
	v_pk_mov_b32 v[74:75], v[2:3], v[2:3]
	v_pk_mov_b32 v[76:77], v[2:3], v[2:3]
	v_pk_mov_b32 v[82:83], v[2:3], v[2:3]
	v_pk_mov_b32 v[84:85], v[2:3], v[2:3]
	v_pk_mov_b32 v[90:91], v[2:3], v[2:3]
	v_pk_mov_b32 v[92:93], v[2:3], v[2:3]
	v_pk_mov_b32 v[98:99], v[2:3], v[2:3]
	v_pk_mov_b32 v[100:101], v[2:3], v[2:3]
	v_pk_mov_b32 v[106:107], v[2:3], v[2:3]
	v_pk_mov_b32 v[108:109], v[2:3], v[2:3]
	v_pk_mov_b32 v[114:115], v[2:3], v[2:3]
	v_pk_mov_b32 v[116:117], v[2:3], v[2:3]
	v_pk_mov_b32 v[78:79], v[2:3], v[2:3]
	v_pk_mov_b32 v[80:81], v[2:3], v[2:3]
	v_pk_mov_b32 v[86:87], v[2:3], v[2:3]
	v_pk_mov_b32 v[88:89], v[2:3], v[2:3]
	v_pk_mov_b32 v[94:95], v[2:3], v[2:3]
	v_pk_mov_b32 v[96:97], v[2:3], v[2:3]
	v_pk_mov_b32 v[102:103], v[2:3], v[2:3]
	v_pk_mov_b32 v[104:105], v[2:3], v[2:3]
	v_pk_mov_b32 v[110:111], v[2:3], v[2:3]
	v_pk_mov_b32 v[112:113], v[2:3], v[2:3]
	v_pk_mov_b32 v[118:119], v[2:3], v[2:3]
	v_pk_mov_b32 v[120:121], v[2:3], v[2:3]
	v_pk_mov_b32 v[122:123], v[2:3], v[2:3]
	v_pk_mov_b32 v[124:125], v[2:3], v[2:3]
	v_pk_mov_b32 v[126:127], v[2:3], v[2:3]
	v_pk_mov_b32 v[128:129], v[2:3], v[2:3]

;     __device__ __forceinline__ bool next(int i, Unit& u) const { if ((long)i * G + c >= nwg) return false; u.pm = 0; u.pn = 0; return true; }
;     ...
;         const bool has_next = S.next(ui + 1, nxt);
;         const char* nA0 = has_next ? (const char*)g.A + (size_t)nxt.pm * tstep : cA; const char* nB0 = has_next ? (const char*)g.Bt + (size_t)nxt.pn * tstep : cB;
;         int nkb = 0; if constexpr (Sched::SK) { if (has_next) nkb = nxt.kb; }
;         const char* nA = nA0 + (size_t)nkb * kstep; const char* nB = nB0 + (size_t)nkb * kstep;
;         for (int t = kb; t < ke; t += 2) {
;             const bool last = (t == ke - 2);
;             const char* a1 = cA + (size_t)(t + 1) * kstep;
;             const char* a2 = last ? nA : cA + (size_t)(t + 2) * kstep; const char* b2 = last ? nB : cB + (size_t)(t + 2) * kstep;
;             const char* a3 = a2 + kstep; const char* b3 = b2 + kstep;
;     ...
; #pragma unroll
;         for (int a = 0; a < 2; ++a)
; #pragma unroll
;             for (int b = 0; b < 2; ++b)
; #pragma unroll
;                 for (int m = 0; m < 4; ++m)
; #pragma unroll
;                     for (int n = 0; n < 2; ++n) acc[a][b][m][n] = (f32x4){0.f, 0.f, 0.f, 0.f};
.LBB0_724:
	s_ashr_i32 s47, s46, 31
	s_lshl_b64 s[26:27], s[46:47], 21
	s_add_u32 s48, s42, s26
	s_addc_u32 s49, s43, s27
	s_and_b64 s[26:27], s[2:3], exec
	s_cselect_b32 s5, s49, s61
	s_cselect_b32 s26, s48, s60
	s_ashr_i32 s23, s22, 31
	s_lshl_b64 s[52:53], s[22:23], 21
	s_add_u32 s52, s36, s52
	s_addc_u32 s53, s37, s53
	s_and_b64 s[64:65], s[2:3], exec
	s_cselect_b32 s23, s53, s63
	s_cselect_b32 s27, s52, s62
	s_add_u32 s60, s60, 0x100080
	s_addc_u32 s61, s61, 0
	s_add_u32 s47, s62, 0x100
	v_mov_b32_e32 v2, 0
	s_addc_u32 s82, s63, 0
	s_mov_b32 s83, -2
	v_mov_b32_e32 v3, v2
	v_pk_mov_b32 v[4:5], v[2:3], v[2:3]
	v_pk_mov_b32 v[6:7], v[2:3], v[2:3]
	v_pk_mov_b32 v[8:9], v[2:3], v[2:3]
	v_pk_mov_b32 v[18:19], v[2:3], v[2:3]
	v_pk_mov_b32 v[20:21], v[2:3], v[2:3]
	v_pk_mov_b32 v[22:23], v[2:3], v[2:3]
	v_pk_mov_b32 v[24:25], v[2:3], v[2:3]
	v_pk_mov_b32 v[34:35], v[2:3], v[2:3]
	v_pk_mov_b32 v[36:37], v[2:3], v[2:3]
	v_pk_mov_b32 v[38:39], v[2:3], v[2:3]
	v_pk_mov_b32 v[40:41], v[2:3], v[2:3]
	v_pk_mov_b32 v[50:51], v[2:3], v[2:3]
	v_pk_mov_b32 v[52:53], v[2:3], v[2:3]
	v_pk_mov_b32 v[54:55], v[2:3], v[2:3]
	v_pk_mov_b32 v[56:57], v[2:3], v[2:3]
	v_pk_mov_b32 v[10:11], v[2:3], v[2:3]
	v_pk_mov_b32 v[12:13], v[2:3], v[2:3]
	v_pk_mov_b32 v[14:15], v[2:3], v[2:3]
	v_pk_mov_b32 v[16:17], v[2:3], v[2:3]
	v_pk_mov_b32 v[26:27], v[2:3], v[2:3]
	v_pk_mov_b32 v[28:29], v[2:3], v[2:3]
	v_pk_mov_b32 v[30:31], v[2:3], v[2:3]
	v_pk_mov_b32 v[32:33], v[2:3], v[2:3]
	v_pk_mov_b32 v[42:43], v[2:3], v[2:3]
	v_pk_mov_b32 v[44:45], v[2:3], v[2:3]
	v_pk_mov_b32 v[46:47], v[2:3], v[2:3]
	v_pk_mov_b32 v[48:49], v[2:3], v[2:3]
	v_pk_mov_b32 v[58:59], v[2:3], v[2:3]
	v_pk_mov_b32 v[60:61], v[2:3], v[2:3]
	v_pk_mov_b32 v[62:63], v[2:3], v[2:3]
	v_pk_mov_b32 v[64:65], v[2:3], v[2:3]
	v_pk_mov_b32 v[66:67], v[2:3], v[2:3]
	v_pk_mov_b32 v[68:69], v[2:3], v[2:3]
	v_pk_mov_b32 v[70:71], v[2:3], v[2:3]
	v_pk_mov_b32 v[72:73], v[2:3], v[2:3]
	v_pk_mov_b32 v[82:83], v[2:3], v[2:3]
	v_pk_mov_b32 v[84:85], v[2:3], v[2:3]
	v_pk_mov_b32 v[86:87], v[2:3], v[2:3]
	v_pk_mov_b32 v[88:89], v[2:3], v[2:3]
	v_pk_mov_b32 v[98:99], v[2:3], v[2:3]
	v_pk_mov_b32 v[100:101], v[2:3], v[2:3]
	v_pk_mov_b32 v[102:103], v[2:3], v[2:3]
	v_pk_mov_b32 v[104:105], v[2:3], v[2:3]
	v_pk_mov_b32 v[114:115], v[2:3], v[2:3]
	v_pk_mov_b32 v[116:117], v[2:3], v[2:3]
	v_pk_mov_b32 v[118:119], v[2:3], v[2:3]
	v_pk_mov_b32 v[120:121], v[2:3], v[2:3]
	v_pk_mov_b32 v[74:75], v[2:3], v[2:3]
	v_pk_mov_b32 v[76:77], v[2:3], v[2:3]
	v_pk_mov_b32 v[78:79], v[2:3], v[2:3]
	v_pk_mov_b32 v[80:81], v[2:3], v[2:3]
	v_pk_mov_b32 v[90:91], v[2:3], v[2:3]
	v_pk_mov_b32 v[92:93], v[2:3], v[2:3]
	v_pk_mov_b32 v[94:95], v[2:3], v[2:3]
	v_pk_mov_b32 v[96:97], v[2:3], v[2:3]
	v_pk_mov_b32 v[106:107], v[2:3], v[2:3]
	v_pk_mov_b32 v[108:109], v[2:3], v[2:3]
	v_pk_mov_b32 v[110:111], v[2:3], v[2:3]
	v_pk_mov_b32 v[112:113], v[2:3], v[2:3]
	v_pk_mov_b32 v[122:123], v[2:3], v[2:3]
	v_pk_mov_b32 v[124:125], v[2:3], v[2:3]
	v_pk_mov_b32 v[126:127], v[2:3], v[2:3]
	v_pk_mov_b32 v[128:129], v[2:3], v[2:3]

;     ...
; #pragma unroll
;         for (int a = 0; a < 2; ++a)
; #pragma unroll
;             for (int b = 0; b < 2; ++b)
; #pragma unroll
;                 for (int m = 0; m < 4; ++m)
; #pragma unroll
;                     for (int n = 0; n < 2; ++n) acc[a][b][m][n] = (f32x4){0.f, 0.f, 0.f, 0.f};
;         cur = nxt; cA = nA0; cB = nB0; ++ui; if constexpr (Sched::SK) { kb = cur.kb; ke = cur.ke; }
.LBB0_912:
	v_mov_b32_e32 v34, 0
	s_mov_b32 s16, s88
	s_mov_b32 s76, s87
	s_mov_b32 s10, s52
	s_mov_b32 s14, s48
	s_mov_b32 s79, s86
	s_mov_b32 s18, s54
	s_mov_b64 s[20:21], s[66:67]
	s_mov_b64 s[22:23], s[64:65]
	s_mov_b32 s80, s89
	v_mov_b32_e32 v35, v34
	v_pk_mov_b32 v[36:37], v[34:35], v[34:35]
	v_pk_mov_b32 v[38:39], v[34:35], v[34:35]
	v_pk_mov_b32 v[40:41], v[34:35], v[34:35]
	v_pk_mov_b32 v[42:43], v[34:35], v[34:35]
	v_pk_mov_b32 v[44:45], v[34:35], v[34:35]
	v_pk_mov_b32 v[46:47], v[34:35], v[34:35]
	v_pk_mov_b32 v[48:49], v[34:35], v[34:35]
	v_pk_mov_b32 v[50:51], v[34:35], v[34:35]
	v_pk_mov_b32 v[52:53], v[34:35], v[34:35]
	v_pk_mov_b32 v[54:55], v[34:35], v[34:35]
	v_pk_mov_b32 v[56:57], v[34:35], v[34:35]
	v_pk_mov_b32 v[58:59], v[34:35], v[34:35]
	v_pk_mov_b32 v[60:61], v[34:35], v[34:35]
	v_pk_mov_b32 v[62:63], v[34:35], v[34:35]
	v_pk_mov_b32 v[64:65], v[34:35], v[34:35]
	v_pk_mov_b32 v[66:67], v[34:35], v[34:35]
	v_pk_mov_b32 v[68:69], v[34:35], v[34:35]
	v_pk_mov_b32 v[70:71], v[34:35], v[34:35]
	v_pk_mov_b32 v[72:73], v[34:35], v[34:35]
	v_pk_mov_b32 v[74:75], v[34:35], v[34:35]
	v_pk_mov_b32 v[76:77], v[34:35], v[34:35]
	v_pk_mov_b32 v[78:79], v[34:35], v[34:35]
	v_pk_mov_b32 v[80:81], v[34:35], v[34:35]
	v_pk_mov_b32 v[82:83], v[34:35], v[34:35]
	v_pk_mov_b32 v[84:85], v[34:35], v[34:35]
	v_pk_mov_b32 v[86:87], v[34:35], v[34:35]
	v_pk_mov_b32 v[88:89], v[34:35], v[34:35]
	v_pk_mov_b32 v[90:91], v[34:35], v[34:35]
	v_pk_mov_b32 v[92:93], v[34:35], v[34:35]
	v_pk_mov_b32 v[94:95], v[34:35], v[34:35]
	v_pk_mov_b32 v[96:97], v[34:35], v[34:35]
	v_pk_mov_b32 v[98:99], v[34:35], v[34:35]
	v_pk_mov_b32 v[100:101], v[34:35], v[34:35]
	v_pk_mov_b32 v[102:103], v[34:35], v[34:35]
	v_pk_mov_b32 v[104:105], v[34:35], v[34:35]
	v_pk_mov_b32 v[106:107], v[34:35], v[34:35]
	v_pk_mov_b32 v[108:109], v[34:35], v[34:35]
	v_pk_mov_b32 v[110:111], v[34:35], v[34:35]
	v_pk_mov_b32 v[112:113], v[34:35], v[34:35]
	v_pk_mov_b32 v[114:115], v[34:35], v[34:35]
	v_pk_mov_b32 v[116:117], v[34:35], v[34:35]
	v_pk_mov_b32 v[118:119], v[34:35], v[34:35]
	v_pk_mov_b32 v[120:121], v[34:35], v[34:35]
	v_pk_mov_b32 v[122:123], v[34:35], v[34:35]
	v_pk_mov_b32 v[124:125], v[34:35], v[34:35]
	v_pk_mov_b32 v[126:127], v[34:35], v[34:35]
	v_pk_mov_b32 v[128:129], v[34:35], v[34:35]
	v_pk_mov_b32 v[130:131], v[34:35], v[34:35]
	v_pk_mov_b32 v[132:133], v[34:35], v[34:35]
	v_pk_mov_b32 v[134:135], v[34:35], v[34:35]
	v_pk_mov_b32 v[136:137], v[34:35], v[34:35]
	v_pk_mov_b32 v[138:139], v[34:35], v[34:35]
	v_pk_mov_b32 v[140:141], v[34:35], v[34:35]
	v_pk_mov_b32 v[142:143], v[34:35], v[34:35]
	v_pk_mov_b32 v[144:145], v[34:35], v[34:35]
	v_pk_mov_b32 v[146:147], v[34:35], v[34:35]
	v_pk_mov_b32 v[148:149], v[34:35], v[34:35]
	v_pk_mov_b32 v[150:151], v[34:35], v[34:35]
	v_pk_mov_b32 v[152:153], v[34:35], v[34:35]
	v_pk_mov_b32 v[154:155], v[34:35], v[34:35]
	v_pk_mov_b32 v[156:157], v[34:35], v[34:35]
	v_pk_mov_b32 v[158:159], v[34:35], v[34:35]
	v_pk_mov_b32 v[160:161], v[34:35], v[34:35]

;     ...
; #pragma unroll
;         for (int a = 0; a < 2; ++a)
; #pragma unroll
;             for (int b = 0; b < 2; ++b)
; #pragma unroll
;                 for (int m = 0; m < 4; ++m)
; #pragma unroll
;                     for (int n = 0; n < 2; ++n) acc[a][b][m][n] = (f32x4){0.f, 0.f, 0.f, 0.f};
;         cur = nxt; cA = nA0; cB = nB0; ++ui; if constexpr (Sched::SK) { kb = cur.kb; ke = cur.ke; }
.LBB0_1024:
	v_mov_b32_e32 v34, 0
	s_mov_b32 s18, s85
	s_mov_b32 s63, s84
	s_mov_b32 s0, s82
	s_mov_b32 s1, s81
	s_mov_b32 s64, s83
	s_mov_b32 s20, s46
	s_mov_b64 s[22:23], s[54:55]
	s_mov_b64 s[24:25], s[52:53]
	s_mov_b32 s76, s86
	v_mov_b32_e32 v35, v34
	v_pk_mov_b32 v[36:37], v[34:35], v[34:35]
	v_pk_mov_b32 v[38:39], v[34:35], v[34:35]
	v_pk_mov_b32 v[40:41], v[34:35], v[34:35]
	v_pk_mov_b32 v[42:43], v[34:35], v[34:35]
	v_pk_mov_b32 v[44:45], v[34:35], v[34:35]
	v_pk_mov_b32 v[46:47], v[34:35], v[34:35]
	v_pk_mov_b32 v[48:49], v[34:35], v[34:35]
	v_pk_mov_b32 v[50:51], v[34:35], v[34:35]
	v_pk_mov_b32 v[52:53], v[34:35], v[34:35]
	v_pk_mov_b32 v[54:55], v[34:35], v[34:35]
	v_pk_mov_b32 v[56:57], v[34:35], v[34:35]
	v_pk_mov_b32 v[58:59], v[34:35], v[34:35]
	v_pk_mov_b32 v[60:61], v[34:35], v[34:35]
	v_pk_mov_b32 v[62:63], v[34:35], v[34:35]
	v_pk_mov_b32 v[64:65], v[34:35], v[34:35]
	v_pk_mov_b32 v[66:67], v[34:35], v[34:35]
	v_pk_mov_b32 v[68:69], v[34:35], v[34:35]
	v_pk_mov_b32 v[70:71], v[34:35], v[34:35]
	v_pk_mov_b32 v[72:73], v[34:35], v[34:35]
	v_pk_mov_b32 v[74:75], v[34:35], v[34:35]
	v_pk_mov_b32 v[76:77], v[34:35], v[34:35]
	v_pk_mov_b32 v[78:79], v[34:35], v[34:35]
	v_pk_mov_b32 v[80:81], v[34:35], v[34:35]
	v_pk_mov_b32 v[82:83], v[34:35], v[34:35]
	v_pk_mov_b32 v[84:85], v[34:35], v[34:35]
	v_pk_mov_b32 v[86:87], v[34:35], v[34:35]
	v_pk_mov_b32 v[88:89], v[34:35], v[34:35]
	v_pk_mov_b32 v[90:91], v[34:35], v[34:35]
	v_pk_mov_b32 v[92:93], v[34:35], v[34:35]
	v_pk_mov_b32 v[94:95], v[34:35], v[34:35]
	v_pk_mov_b32 v[96:97], v[34:35], v[34:35]
	v_pk_mov_b32 v[98:99], v[34:35], v[34:35]
	v_pk_mov_b32 v[100:101], v[34:35], v[34:35]
	v_pk_mov_b32 v[102:103], v[34:35], v[34:35]
	v_pk_mov_b32 v[104:105], v[34:35], v[34:35]
	v_pk_mov_b32 v[106:107], v[34:35], v[34:35]
	v_pk_mov_b32 v[108:109], v[34:35], v[34:35]
	v_pk_mov_b32 v[110:111], v[34:35], v[34:35]
	v_pk_mov_b32 v[112:113], v[34:35], v[34:35]
	v_pk_mov_b32 v[114:115], v[34:35], v[34:35]
	v_pk_mov_b32 v[116:117], v[34:35], v[34:35]
	v_pk_mov_b32 v[118:119], v[34:35], v[34:35]
	v_pk_mov_b32 v[120:121], v[34:35], v[34:35]
	v_pk_mov_b32 v[122:123], v[34:35], v[34:35]
	v_pk_mov_b32 v[124:125], v[34:35], v[34:35]
	v_pk_mov_b32 v[126:127], v[34:35], v[34:35]
	v_pk_mov_b32 v[128:129], v[34:35], v[34:35]
	v_pk_mov_b32 v[130:131], v[34:35], v[34:35]
	v_pk_mov_b32 v[132:133], v[34:35], v[34:35]
	v_pk_mov_b32 v[134:135], v[34:35], v[34:35]
	v_pk_mov_b32 v[136:137], v[34:35], v[34:35]
	v_pk_mov_b32 v[138:139], v[34:35], v[34:35]
	v_pk_mov_b32 v[140:141], v[34:35], v[34:35]
	v_pk_mov_b32 v[142:143], v[34:35], v[34:35]
	v_pk_mov_b32 v[144:145], v[34:35], v[34:35]
	v_pk_mov_b32 v[146:147], v[34:35], v[34:35]
	v_pk_mov_b32 v[148:149], v[34:35], v[34:35]
	v_pk_mov_b32 v[150:151], v[34:35], v[34:35]
	v_pk_mov_b32 v[152:153], v[34:35], v[34:35]
	v_pk_mov_b32 v[154:155], v[34:35], v[34:35]
	v_pk_mov_b32 v[156:157], v[34:35], v[34:35]
	v_pk_mov_b32 v[158:159], v[34:35], v[34:35]
	v_pk_mov_b32 v[160:161], v[34:35], v[34:35]
